# v9: v7 + P5/P8 gain-vector preambles: all loads issued first, copy loops fed from registers (6 -> 1 serialized round trips in P5)
# speedup vs baseline: 1.0039x; 1.0039x over previous
.LBB0_696:
	s_or_b64 exec, exec, s[4:5]
	s_mov_b32 s4, 0
	s_waitcnt lgkmcnt(0)
	s_barrier
	s_mov_b64 s[22:23], s[0:1]
	v_mbcnt_lo_u32_b32 v0, -1, s4
	v_mbcnt_hi_u32_b32 v2, -1, v0
	s_mov_b32 s2, 0
	s_load_dwordx4 s[16:19], s[22:23], 0x80
	s_nop 0
	v_mbcnt_lo_u32_b32 v0, -1, s2
	v_mbcnt_hi_u32_b32 v0, -1, v0
	v_add_u32_e32 v0, s33, v0
	s_movk_i32 s2, 0x400
	s_nop 0
	v_cmp_gt_i32_e32 vcc, s2, v0
	s_and_saveexec_b64 s[10:11], vcc
	s_cbranch_execz .LBB0_703
	s_load_dwordx4 s[4:7], s[22:23], 0x48
	s_load_dwordx2 s[8:9], s[22:23], 0x58
	v_ashrrev_i32_e32 v1, 31, v0
	v_add_u32_e32 v3, 0xfffffe00, v0
	v_lshlrev_b32_e32 v6, 4, v0
	v_lshlrev_b64 v[0:1], 4, v[0:1]
	v_add_u32_e32 v7, 0, v6
	s_waitcnt lgkmcnt(0)
	v_lshl_add_u64 v[4:5], s[6:7], 0, v[0:1]
	s_mov_b64 s[86:87], 0x2000
	v_lshl_add_u64 v[224:225], s[8:9], 0, v[0:1]
	v_lshl_add_u64 v[226:227], s[4:5], 0, v[0:1]
	v_lshl_add_u64 v[228:229], v[4:5], 0, s[86:87]
	v_lshl_add_u64 v[230:231], v[224:225], 0, s[86:87]
	v_lshl_add_u64 v[232:233], v[226:227], 0, s[86:87]
	global_load_dwordx4 v[200:203], v[4:5], off
	global_load_dwordx4 v[204:207], v[228:229], off
	global_load_dwordx4 v[208:211], v[224:225], off
	global_load_dwordx4 v[212:215], v[230:231], off
	global_load_dwordx4 v[216:219], v[226:227], off
	global_load_dwordx4 v[220:223], v[232:233], off
	s_mov_b64 s[6:7], 0
	s_mov_b64 s[22:23], 0x2000
	s_movk_i32 s2, 0x1ff
	v_mov_b32_e32 v8, v3
.LBB0_698:
	s_waitcnt vmcnt(4)
	v_mov_b32_e32 v10, v200
	v_mov_b32_e32 v11, v201
	v_mov_b32_e32 v12, v202
	v_mov_b32_e32 v13, v203
	v_mov_b32_e32 v200, v204
	v_mov_b32_e32 v201, v205
	v_mov_b32_e32 v202, v206
	v_mov_b32_e32 v203, v207
	v_add_u32_e32 v8, 0x200, v8
	v_cmp_lt_i32_e32 vcc, s2, v8
	v_lshl_add_u64 v[4:5], v[4:5], 0, s[22:23]
	s_or_b64 s[6:7], vcc, s[6:7]
	s_nop 0
	ds_write_b128 v7, v[10:13]
	v_add_u32_e32 v7, 0x2000, v7
	s_andn2_b64 exec, exec, s[6:7]
	s_cbranch_execnz .LBB0_698
	s_or_b64 exec, exec, s[6:7]
	v_add_u32_e32 v6, 0, v6
	v_add_u32_e32 v7, 0x4000, v6
	v_lshl_add_u64 v[4:5], s[8:9], 0, v[0:1]
	s_mov_b64 s[6:7], 0
	s_mov_b64 s[8:9], 0x2000
	s_movk_i32 s2, 0x1ff
	v_mov_b32_e32 v8, v3
.LBB0_700:
	s_waitcnt vmcnt(2)
	v_mov_b32_e32 v10, v208
	v_mov_b32_e32 v11, v209
	v_mov_b32_e32 v12, v210
	v_mov_b32_e32 v13, v211
	v_mov_b32_e32 v208, v212
	v_mov_b32_e32 v209, v213
	v_mov_b32_e32 v210, v214
	v_mov_b32_e32 v211, v215
	v_add_u32_e32 v8, 0x200, v8
	v_cmp_lt_i32_e32 vcc, s2, v8
	v_lshl_add_u64 v[4:5], v[4:5], 0, s[8:9]
	s_or_b64 s[6:7], vcc, s[6:7]
	s_nop 0
	ds_write_b128 v7, v[10:13]
	v_add_u32_e32 v7, 0x2000, v7
	s_andn2_b64 exec, exec, s[6:7]
	s_cbranch_execnz .LBB0_700
	s_or_b64 exec, exec, s[6:7]
	v_add_u32_e32 v4, 0x8000, v6
	v_lshl_add_u64 v[0:1], s[4:5], 0, v[0:1]
	s_mov_b64 s[22:23], 0
	s_mov_b64 s[24:25], 0x2000
	s_movk_i32 s2, 0x1ff
.LBB0_702:
	s_waitcnt vmcnt(0)
	v_mov_b32_e32 v6, v216
	v_mov_b32_e32 v7, v217
	v_mov_b32_e32 v8, v218
	v_mov_b32_e32 v9, v219
	v_mov_b32_e32 v216, v220
	v_mov_b32_e32 v217, v221
	v_mov_b32_e32 v218, v222
	v_mov_b32_e32 v219, v223
	v_add_u32_e32 v3, 0x200, v3
	v_cmp_lt_i32_e32 vcc, s2, v3
	s_or_b64 s[22:23], vcc, s[22:23]
	v_lshl_add_u64 v[0:1], v[0:1], 0, s[24:25]
	s_nop 0
	v_div_scale_f32 v5, s[4:5], v6, v6, 1.0
	v_div_scale_f32 v11, s[4:5], v7, v7, 1.0
	v_rcp_f32_e32 v17, v5
	v_div_scale_f32 v13, s[6:7], v8, v8, 1.0
	v_rcp_f32_e32 v18, v11
	v_div_scale_f32 v15, s[8:9], v9, v9, 1.0
	v_rcp_f32_e32 v19, v13
	v_rcp_f32_e32 v20, v15
	v_fma_f32 v21, -v5, v17, 1.0
	v_div_scale_f32 v10, vcc, 1.0, v6, 1.0
	v_fma_f32 v22, -v11, v18, 1.0
	v_fmac_f32_e32 v17, v21, v17
	v_div_scale_f32 v12, s[4:5], 1.0, v7, 1.0
	v_fma_f32 v23, -v13, v19, 1.0
	v_fmac_f32_e32 v18, v22, v18
	v_mul_f32_e32 v21, v10, v17
	v_div_scale_f32 v14, s[6:7], 1.0, v8, 1.0
	v_fma_f32 v24, -v15, v20, 1.0
	v_fmac_f32_e32 v19, v23, v19
	v_mul_f32_e32 v22, v12, v18
	v_fma_f32 v25, -v5, v21, v10
	v_div_scale_f32 v16, s[8:9], 1.0, v9, 1.0
	v_fmac_f32_e32 v20, v24, v20
	v_mul_f32_e32 v23, v14, v19
	v_fma_f32 v26, -v11, v22, v12
	v_fmac_f32_e32 v21, v25, v17
	v_mul_f32_e32 v24, v16, v20
	v_fma_f32 v27, -v13, v23, v14
	v_fmac_f32_e32 v22, v26, v18
	v_fma_f32 v5, -v5, v21, v10
	v_fma_f32 v28, -v15, v24, v16
	v_fmac_f32_e32 v23, v27, v19
	v_fma_f32 v10, -v11, v22, v12
	v_div_fmas_f32 v5, v5, v17, v21
	s_mov_b64 vcc, s[4:5]
	v_fmac_f32_e32 v24, v28, v20
	v_fma_f32 v11, -v13, v23, v14
	v_div_fixup_f32 v6, v5, v6, 1.0
	v_div_fmas_f32 v5, v10, v18, v22
	s_mov_b64 vcc, s[6:7]
	v_fma_f32 v12, -v15, v24, v16
	v_div_fixup_f32 v7, v5, v7, 1.0
	v_div_fmas_f32 v5, v11, v19, v23
	s_mov_b64 vcc, s[8:9]
	v_div_fixup_f32 v8, v5, v8, 1.0
	v_div_fmas_f32 v5, v12, v20, v24
	v_div_fixup_f32 v9, v5, v9, 1.0
	ds_write_b128 v4, v[6:9]
	v_add_u32_e32 v4, 0x2000, v4
	s_andn2_b64 exec, exec, s[22:23]
	s_cbranch_execnz .LBB0_702

.LBB0_1039:
	s_or_b64 exec, exec, s[2:3]
	s_mov_b32 s3, 0
	s_waitcnt lgkmcnt(0)
	s_barrier
	s_mov_b32 s2, 0
	v_mbcnt_lo_u32_b32 v0, -1, s3
	v_mbcnt_hi_u32_b32 v0, -1, v0
	s_load_dwordx4 s[8:11], s[0:1], 0x80
	s_nop 0
	v_mbcnt_lo_u32_b32 v1, -1, s2
	v_mbcnt_hi_u32_b32 v1, -1, v1
	v_add_u32_e32 v2, s33, v1
	s_movk_i32 s2, 0x400
	s_nop 0
	v_cmp_gt_i32_e32 vcc, s2, v2
	s_and_saveexec_b64 s[2:3], vcc
	s_cbranch_execz .LBB0_1042
	s_load_dwordx2 s[6:7], s[0:1], 0x60
	v_ashrrev_i32_e32 v3, 31, v2
	v_add_u32_e32 v1, 0xfffffe00, v2
	v_lshl_add_u32 v4, v2, 4, 0
	s_mov_b64 s[0:1], 0
	s_waitcnt lgkmcnt(0)
	v_lshl_add_u64 v[2:3], v[2:3], 4, s[6:7]
	s_mov_b64 s[6:7], 0x2000
	v_lshl_add_u64 v[228:229], v[2:3], 0, s[6:7]
	global_load_dwordx4 v[200:203], v[2:3], off
	global_load_dwordx4 v[204:207], v[228:229], off
	s_movk_i32 s12, 0x1ff
.LBB0_1041:
	s_waitcnt vmcnt(0)
	v_mov_b32_e32 v6, v200
	v_mov_b32_e32 v7, v201
	v_mov_b32_e32 v8, v202
	v_mov_b32_e32 v9, v203
	v_mov_b32_e32 v200, v204
	v_mov_b32_e32 v201, v205
	v_mov_b32_e32 v202, v206
	v_mov_b32_e32 v203, v207
	v_add_u32_e32 v1, 0x200, v1
	v_cmp_lt_i32_e32 vcc, s12, v1
	v_lshl_add_u64 v[2:3], v[2:3], 0, s[6:7]
	s_or_b64 s[0:1], vcc, s[0:1]
	s_nop 0
	ds_write_b128 v4, v[6:9]
	v_add_u32_e32 v4, 0x2000, v4
	s_andn2_b64 exec, exec, s[0:1]
	s_cbranch_execnz .LBB0_1041
